# mix rebalance with the overloaded workgroups spread over all XCDs (16 per XCD) instead of filling XCD 0-1
# baseline (speedup 1.0000x reference)
.LBB0_645:
	s_mov_b32 s101, s85
	s_cmpk_lg_u32 s33, 0x200
	s_cbranch_scc1 .Lop_done
	s_and_b32 s98, s85, 63
	s_lshr_b32 s99, s85, 6
	s_cmpk_lt_u32 s98, 16
	s_cbranch_scc0 .Lop_hi
	s_lshl_b32 s101, s99, 4
	s_add_i32 s101, s101, s98
	s_branch .Lop_done
.Lop_hi:
	s_mul_i32 s101, s99, 48
	s_add_i32 s101, s101, s98
	s_add_i32 s101, s101, 0x70
.Lop_done:
	s_add_i32 s54, s62, s101
	s_cmpk_lg_u32 s33, 0x200
	s_cbranch_scc1 .Lmixbal_done
	s_cmpk_lt_u32 s101, 0x80
	s_cbranch_scc0 .Lmixbal_hi
	s_sub_i32 s98, s62, 0xe00
	s_cmpk_gt_u32 s98, 0x400
	s_cbranch_scc1 .Lmixbal_done
	s_lshr_b32 s98, s98, 2
	s_add_i32 s54, s101, 0x1480
	s_add_i32 s54, s54, s98
	s_branch .Lmixbal_done
.Lmixbal_hi:
	s_cmpk_lg_u32 s62, 0x1400
	s_cbranch_scc1 .Lmixbal_done
	s_sub_i32 s98, s101, 0x80
	s_lshr_b32 s99, s98, 7
	s_lshl_b32 s99, s99, 9
	s_and_b32 s98, s98, 0x7f
	s_add_i32 s54, s98, s99
	s_add_i32 s54, s54, 0xe00
